# quarter-unit K loop: MFMA block moved before the first barrier of each half-step with the fragment-read wait in front of that barrier (restores the wave-group stagger rule for LDS-DMA refills); same p
# baseline (speedup 1.0000x reference)
.Lq5_top:
	ds_read_b128 v[148:151], v214
	ds_read_b128 v[152:155], v214 offset:1024
	ds_read_b128 v[156:159], v214 offset:2048
	ds_read_b128 v[160:163], v214 offset:3072
	v_lshl_add_u64 v[2:3], s[34:35], 0, v[200:201]
	s_add_i32 m0, s48, 0xc000
	ds_read_b128 v[188:191], v216
	ds_read_b128 v[192:195], v216 offset:1024
	ds_read_b128 v[180:183], v216 offset:2048
	ds_read_b128 v[184:187], v216 offset:3072
	ds_read_b128 v[172:175], v216 offset:4096
	ds_read_b128 v[176:179], v216 offset:5120
	ds_read_b128 v[164:167], v216 offset:6144
	ds_read_b128 v[168:171], v216 offset:7168
	v_lshl_add_u64 v[2:3], s[34:35], 0, v[202:203]
	s_add_i32 m0, s48, 0xe000
	s_nop 0
	s_waitcnt vmcnt(4)
	s_setprio 1
	v_mfma_f32_16x16x32_bf16 v[128:131], v[4:7], v[44:47], v[128:131]
	v_mfma_f32_16x16x32_bf16 v[124:127], v[12:15], v[44:47], v[124:127]
	v_mfma_f32_16x16x32_bf16 v[120:123], v[4:7], v[36:39], v[120:123]
	v_mfma_f32_16x16x32_bf16 v[116:119], v[12:15], v[36:39], v[116:119]
	v_mfma_f32_16x16x32_bf16 v[104:107], v[4:7], v[28:31], v[104:107]
	v_mfma_f32_16x16x32_bf16 v[100:103], v[12:15], v[28:31], v[100:103]
	v_mfma_f32_16x16x32_bf16 v[88:91], v[4:7], v[20:23], v[88:91]
	v_mfma_f32_16x16x32_bf16 v[84:87], v[12:15], v[20:23], v[84:87]
	v_mfma_f32_16x16x32_bf16 v[128:131], v[8:11], v[48:51], v[128:131]
	v_mfma_f32_16x16x32_bf16 v[124:127], v[16:19], v[48:51], v[124:127]
	v_mfma_f32_16x16x32_bf16 v[120:123], v[8:11], v[40:43], v[120:123]
	v_mfma_f32_16x16x32_bf16 v[116:119], v[16:19], v[40:43], v[116:119]
	v_mfma_f32_16x16x32_bf16 v[104:107], v[8:11], v[32:35], v[104:107]
	v_mfma_f32_16x16x32_bf16 v[100:103], v[16:19], v[32:35], v[100:103]
	v_mfma_f32_16x16x32_bf16 v[88:91], v[8:11], v[24:27], v[88:91]
	v_mfma_f32_16x16x32_bf16 v[84:87], v[16:19], v[24:27], v[84:87]
	s_waitcnt lgkmcnt(0)
	s_barrier
	s_setprio 0
	v_cmp_ne_u32_e64 s[2:3], 1, v217
	s_andn2_b64 vcc, exec, s[26:27]
	s_add_u32 s56, s34, 0xfff80080
	s_addc_u32 s57, s35, -1
	s_cmp_eq_u32 s77, 12
	s_cselect_b32 s59, s39, s57
	s_cselect_b32 s58, s38, s56
	s_cselect_b32 s57, s47, s41
	s_cselect_b32 s56, s46, s18
	s_barrier
	s_mov_b32 m0, s49
	v_lshl_add_u64 v[2:3], s[56:57], 0, v[198:199]
	s_add_u32 s78, s56, 0x80000
	global_load_lds_dwordx4 v[2:3], off
	v_lshl_add_u64 v[204:205], s[56:57], 0, v[196:197]
	s_mov_b32 m0, s50
	s_addc_u32 s79, s57, 0
	global_load_lds_dwordx4 v[204:205], off
	v_lshl_add_u64 v[206:207], s[78:79], 0, v[198:199]
	s_mov_b32 m0, s51
	v_lshl_add_u64 v[208:209], s[58:59], 0, v[196:197]
	v_lshl_add_u64 v[206:207], s[78:79], 0, v[196:197]
	s_mov_b32 m0, s60
	s_and_b64 vcc, exec, s[2:3]
	v_lshl_add_u64 v[206:207], s[58:59], 0, v[198:199]
	s_mov_b32 m0, s48
	s_nop 0
	global_load_lds_dwordx4 v[206:207], off
	s_mov_b32 m0, s61
	s_nop 0
	global_load_lds_dwordx4 v[208:209], off
	s_waitcnt vmcnt(4)
	s_waitcnt lgkmcnt(0)
	s_barrier
	s_barrier
	v_add_u32_e32 v1, 0x18000, v213
	ds_read_b128 v[4:7], v1
	ds_read_b128 v[8:11], v1 offset:1024
	ds_read_b128 v[12:15], v1 offset:2048
	ds_read_b128 v[16:19], v1 offset:3072
	v_add_u32_e32 v1, 0x1c000, v213
	s_add_u32 s58, s58, 0x80000
	s_addc_u32 s59, s59, 0
	s_mov_b32 m0, s62
	v_lshl_add_u64 v[218:219], s[58:59], 0, v[198:199]
	ds_read_b128 v[44:47], v216 offset:32768
	ds_read_b128 v[48:51], v216 offset:33792
	ds_read_b128 v[36:39], v216 offset:34816
	ds_read_b128 v[40:43], v216 offset:35840
	ds_read_b128 v[28:31], v216 offset:36864
	ds_read_b128 v[32:35], v216 offset:37888
	ds_read_b128 v[20:23], v216 offset:38912
	ds_read_b128 v[24:27], v216 offset:39936
	v_lshl_add_u64 v[218:219], s[58:59], 0, v[196:197]
	s_mov_b32 m0, s63
	s_nop 0
	s_waitcnt vmcnt(4)
	s_setprio 1
	v_mfma_f32_16x16x32_bf16 v[128:131], v[148:151], v[188:191], v[128:131]
	v_mfma_f32_16x16x32_bf16 v[124:127], v[156:159], v[188:191], v[124:127]
	v_mfma_f32_16x16x32_bf16 v[120:123], v[148:151], v[180:183], v[120:123]
	v_mfma_f32_16x16x32_bf16 v[116:119], v[156:159], v[180:183], v[116:119]
	v_mfma_f32_16x16x32_bf16 v[104:107], v[148:151], v[172:175], v[104:107]
	v_mfma_f32_16x16x32_bf16 v[100:103], v[156:159], v[172:175], v[100:103]
	v_mfma_f32_16x16x32_bf16 v[88:91], v[148:151], v[164:167], v[88:91]
	v_mfma_f32_16x16x32_bf16 v[84:87], v[156:159], v[164:167], v[84:87]
	v_mfma_f32_16x16x32_bf16 v[128:131], v[152:155], v[192:195], v[128:131]
	v_mfma_f32_16x16x32_bf16 v[124:127], v[160:163], v[192:195], v[124:127]
	v_mfma_f32_16x16x32_bf16 v[120:123], v[152:155], v[184:187], v[120:123]
	v_mfma_f32_16x16x32_bf16 v[116:119], v[160:163], v[184:187], v[116:119]
	v_mfma_f32_16x16x32_bf16 v[104:107], v[152:155], v[176:179], v[104:107]
	v_mfma_f32_16x16x32_bf16 v[100:103], v[160:163], v[176:179], v[100:103]
	v_mfma_f32_16x16x32_bf16 v[88:91], v[152:155], v[168:171], v[88:91]
	v_mfma_f32_16x16x32_bf16 v[84:87], v[160:163], v[168:171], v[84:87]
	s_waitcnt lgkmcnt(0)
	s_barrier
	s_setprio 0
	s_and_b64 vcc, exec, s[2:3]
	s_barrier
	s_mov_b32 m0, s66
	v_lshl_add_u64 v[2:3], v[2:3], 0, s[16:17]
	s_add_u32 s56, s56, 0x80080
	global_load_lds_dwordx4 v[2:3], off
	v_lshl_add_u64 v[2:3], v[204:205], 0, s[16:17]
	s_mov_b32 m0, s67
	s_addc_u32 s57, s57, 0
	global_load_lds_dwordx4 v[2:3], off
	v_lshl_add_u64 v[2:3], s[56:57], 0, v[198:199]
	s_mov_b32 m0, s70
	s_and_b64 vcc, exec, s[2:3]
	v_lshl_add_u64 v[2:3], s[56:57], 0, v[196:197]
	s_mov_b32 m0, s71
	s_nop 0
	v_lshl_add_u64 v[2:3], v[206:207], 0, s[16:17]
	s_mov_b32 m0, s68
	s_nop 0
	global_load_lds_dwordx4 v[2:3], off
	v_lshl_add_u64 v[2:3], v[208:209], 0, s[16:17]
	s_mov_b32 m0, s69
	s_nop 0
	global_load_lds_dwordx4 v[2:3], off
	s_waitcnt vmcnt(4)
	s_waitcnt lgkmcnt(0)
	s_barrier
	s_branch .Lq5_be

.Lq6_top:
	ds_read_b128 v[180:183], v247
	ds_read_b128 v[184:187], v247 offset:1024
	ds_read_b128 v[188:191], v247 offset:2048
	ds_read_b128 v[192:195], v247 offset:3072
	v_lshl_add_u64 v[2:3], s[38:39], 0, v[232:233]
	s_add_i32 m0, s44, 0xc000
	ds_read_b128 v[220:223], v249
	ds_read_b128 v[224:227], v249 offset:1024
	ds_read_b128 v[212:215], v249 offset:2048
	ds_read_b128 v[216:219], v249 offset:3072
	ds_read_b128 v[204:207], v249 offset:4096
	ds_read_b128 v[208:211], v249 offset:5120
	ds_read_b128 v[196:199], v249 offset:6144
	ds_read_b128 v[200:203], v249 offset:7168
	v_lshl_add_u64 v[2:3], s[38:39], 0, v[234:235]
	s_add_i32 m0, s44, 0xe000
	s_nop 0
	s_waitcnt vmcnt(4)
	s_setprio 1
	v_mfma_f32_16x16x32_bf16 v[68:71], v[4:7], v[44:47], v[160:163]
	v_mfma_f32_16x16x32_bf16 v[72:75], v[12:15], v[44:47], v[156:159]
	v_mfma_f32_16x16x32_bf16 v[76:79], v[4:7], v[36:39], v[152:155]
	v_mfma_f32_16x16x32_bf16 v[80:83], v[12:15], v[36:39], v[148:151]
	v_mfma_f32_16x16x32_bf16 v[84:87], v[4:7], v[28:31], v[136:139]
	v_mfma_f32_16x16x32_bf16 v[92:95], v[12:15], v[28:31], v[132:135]
	v_mfma_f32_16x16x32_bf16 v[96:99], v[4:7], v[20:23], v[120:123]
	v_mfma_f32_16x16x32_bf16 v[100:103], v[12:15], v[20:23], v[112:115]
	v_mfma_f32_16x16x32_bf16 v[68:71], v[8:11], v[48:51], v[68:71]
	v_mfma_f32_16x16x32_bf16 v[72:75], v[16:19], v[48:51], v[72:75]
	v_mfma_f32_16x16x32_bf16 v[76:79], v[8:11], v[40:43], v[76:79]
	v_mfma_f32_16x16x32_bf16 v[80:83], v[16:19], v[40:43], v[80:83]
	v_mfma_f32_16x16x32_bf16 v[84:87], v[8:11], v[32:35], v[84:87]
	v_mfma_f32_16x16x32_bf16 v[92:95], v[16:19], v[32:35], v[92:95]
	v_mfma_f32_16x16x32_bf16 v[96:99], v[8:11], v[24:27], v[96:99]
	v_mfma_f32_16x16x32_bf16 v[100:103], v[16:19], v[24:27], v[100:103]
	s_waitcnt lgkmcnt(0)
	s_barrier
	s_setprio 0
	v_cmp_ne_u32_e64 s[4:5], 1, v251
	s_andn2_b64 vcc, exec, s[34:35]
	s_add_u32 s40, s38, 0xfff80080
	s_addc_u32 s41, s39, -1
	s_cmp_eq_u32 s84, 28
	s_cselect_b32 s47, s29, s41
	s_cselect_b32 s46, s28, s40
	s_cselect_b32 s41, s37, s27
	s_cselect_b32 s40, s36, s16
	s_barrier
	s_mov_b32 m0, s45
	v_lshl_add_u64 v[2:3], s[40:41], 0, v[230:231]
	s_add_u32 s86, s40, 0x80000
	global_load_lds_dwordx4 v[2:3], off
	v_lshl_add_u64 v[236:237], s[40:41], 0, v[228:229]
	s_mov_b32 m0, s48
	s_addc_u32 s87, s41, 0
	global_load_lds_dwordx4 v[236:237], off
	v_lshl_add_u64 v[54:55], s[86:87], 0, v[230:231]
	s_mov_b32 m0, s49
	v_lshl_add_u64 v[238:239], s[46:47], 0, v[230:231]
	v_lshl_add_u64 v[54:55], s[86:87], 0, v[228:229]
	s_mov_b32 m0, s50
	v_lshl_add_u64 v[240:241], s[46:47], 0, v[228:229]
	s_mov_b32 m0, s44
	s_and_b64 vcc, exec, s[4:5]
	global_load_lds_dwordx4 v[238:239], off
	s_mov_b32 m0, s51
	s_nop 0
	global_load_lds_dwordx4 v[240:241], off
	s_waitcnt vmcnt(4)
	s_waitcnt lgkmcnt(0)
	s_barrier
	s_barrier
	v_add_u32_e32 v1, 0x18000, v246
	ds_read_b128 v[4:7], v1
	ds_read_b128 v[8:11], v1 offset:1024
	ds_read_b128 v[12:15], v1 offset:2048
	ds_read_b128 v[16:19], v1 offset:3072
	v_add_u32_e32 v1, 0x1c000, v246
	s_add_u32 s46, s46, 0x80000
	s_addc_u32 s47, s47, 0
	s_mov_b32 m0, s56
	v_lshl_add_u64 v[112:113], s[46:47], 0, v[230:231]
	ds_read_b128 v[44:47], v249 offset:32768
	ds_read_b128 v[48:51], v249 offset:33792
	ds_read_b128 v[36:39], v249 offset:34816
	ds_read_b128 v[40:43], v249 offset:35840
	ds_read_b128 v[28:31], v249 offset:36864
	ds_read_b128 v[32:35], v249 offset:37888
	ds_read_b128 v[20:23], v249 offset:38912
	ds_read_b128 v[24:27], v249 offset:39936
	v_lshl_add_u64 v[112:113], s[46:47], 0, v[228:229]
	s_mov_b32 m0, s57
	s_nop 0
	s_waitcnt vmcnt(4)
	s_setprio 1
	v_mfma_f32_16x16x32_bf16 v[68:71], v[180:183], v[220:223], v[68:71]
	v_mfma_f32_16x16x32_bf16 v[160:163], v[184:187], v[224:227], v[68:71]
	v_mfma_f32_16x16x32_bf16 v[68:71], v[188:191], v[220:223], v[72:75]
	v_mfma_f32_16x16x32_bf16 v[156:159], v[192:195], v[224:227], v[68:71]
	v_mfma_f32_16x16x32_bf16 v[68:71], v[180:183], v[212:215], v[76:79]
	v_mfma_f32_16x16x32_bf16 v[152:155], v[184:187], v[216:219], v[68:71]
	v_mfma_f32_16x16x32_bf16 v[68:71], v[188:191], v[212:215], v[80:83]
	v_mfma_f32_16x16x32_bf16 v[148:151], v[192:195], v[216:219], v[68:71]
	v_mfma_f32_16x16x32_bf16 v[68:71], v[180:183], v[204:207], v[84:87]
	v_mfma_f32_16x16x32_bf16 v[136:139], v[184:187], v[208:211], v[68:71]
	v_mfma_f32_16x16x32_bf16 v[68:71], v[188:191], v[204:207], v[92:95]
	v_mfma_f32_16x16x32_bf16 v[132:135], v[192:195], v[208:211], v[68:71]
	v_mfma_f32_16x16x32_bf16 v[68:71], v[180:183], v[196:199], v[96:99]
	v_mfma_f32_16x16x32_bf16 v[120:123], v[184:187], v[200:203], v[68:71]
	v_mfma_f32_16x16x32_bf16 v[68:71], v[188:191], v[196:199], v[100:103]
	v_mfma_f32_16x16x32_bf16 v[112:115], v[192:195], v[200:203], v[68:71]
	s_waitcnt lgkmcnt(0)
	s_barrier
	s_setprio 0
	s_and_b64 vcc, exec, s[4:5]
	s_barrier
	s_mov_b32 m0, s61
	v_lshl_add_u64 v[2:3], v[2:3], 0, s[14:15]
	s_add_u32 s40, s40, 0x80080
	global_load_lds_dwordx4 v[2:3], off
	v_lshl_add_u64 v[2:3], v[236:237], 0, s[14:15]
	s_mov_b32 m0, s62
	s_addc_u32 s41, s41, 0
	global_load_lds_dwordx4 v[2:3], off
	v_lshl_add_u64 v[2:3], s[40:41], 0, v[230:231]
	s_mov_b32 m0, s65
	s_and_b64 vcc, exec, s[4:5]
	v_lshl_add_u64 v[2:3], s[40:41], 0, v[228:229]
	s_mov_b32 m0, s66
	s_nop 0
	v_lshl_add_u64 v[2:3], v[238:239], 0, s[14:15]
	s_mov_b32 m0, s63
	s_nop 0
	global_load_lds_dwordx4 v[2:3], off
	v_lshl_add_u64 v[2:3], v[240:241], 0, s[14:15]
	s_mov_b32 m0, s64
	s_nop 0
	global_load_lds_dwordx4 v[2:3], off
	s_waitcnt vmcnt(4)
	s_waitcnt lgkmcnt(0)
	s_barrier
	s_branch .Lq6_be
